# hand-allocated attention loop: fixed accumulators, in-place exp/cvt, no phi copies
# speedup vs baseline: 1.0268x; 1.0268x over previous
; DEV void attn_item(const P& p, int bh, int qrow0, int nkt, int outrow0, char* smem) {
;     ...
;   int vo = 0; asm volatile("" : "+v"(vo));
;   bf16x8 qf[2][3];
; #pragma unroll
;   for (int qt = 0; qt < 2; ++qt)
; #pragma unroll
;     for (int ks = 0; ks < 3; ++ks) qf[qt][ks] = *(const bf16x8*)(Qb + (size_t)(qrow0 + wid * 32 + qt * 16 + l15) * 96 + ks * 32 + lq * 8);
;   f32x4 o[4][2];
; #pragma unroll
;   for (int vt = 0; vt < 4; ++vt)
; #pragma unroll
;     for (int qt = 0; qt < 2; ++qt) o[vt][qt] = (f32x4){0.f, 0.f, 0.f, 0.f};
;   float mused[2] = {0.f, 0.f};
;   f32x4 osum[2] = {(f32x4){0.f, 0.f, 0.f, 0.f}, (f32x4){0.f, 0.f, 0.f, 0.f}};
;   const bf16x8 ones = __builtin_bit_cast(bf16x8, (u32x4){0x3f803f80u, 0x3f803f80u, 0x3f803f80u, 0x3f803f80u});
;   u32x4 kr[4], vr[2];
;   const int krow = tid >> 4, kc = tid & 15;
;   const int vrow = tid >> 3, vc = tid & 7;
;   const int kwo = vo + krow * 256 + ((kc ^ (krow & 15)) << 4), vwo = vo + VBASE + vrow * 128 + ((vc ^ ((vrow >> 1) & 7)) << 4);
;   const int kro = vo + l15 * 256, vro = vo + VBASE + l15 * 128;
;   f32x4 st[4][2];
;   bf16x8 pf[2][2], vf[2][4];
.LBB0_158:
	s_waitcnt lgkmcnt(0)
	s_barrier
	s_cmpk_gt_u32 s6, 0xff
	v_lshrrev_b32_e32 v1, 1, v207
	v_lshl_add_u32 v210, v207, 7, v4
	s_cselect_b64 s[4:5], -1, 0
	s_cmp_lt_i32 s23, 1
	v_xor_b32_e32 v211, v206, v1
	v_bitop3_b32 v208, v206, v1, 4 bitop3:0x36
	s_cbranch_scc1 .LBB0_214
	v_mov_b32_e32 v1, v41
	v_lshl_add_u64 v[204:205], s[2:3], 0, v[0:1]
	v_xor_b32_e32 v0, v206, v207
	v_lshlrev_b32_e32 v217, 4, v0
	v_bitop3_b32 v0, v206, v207, 4 bitop3:0x36
	v_mov_b32_e32 v42, v41
	v_mov_b32_e32 v43, v41
	v_lshlrev_b32_e32 v218, 4, v0
	v_bitop3_b32 v0, v206, v207, 8 bitop3:0x36
	v_mov_b32_e32 v40, v41
	v_mov_b32_e32 v221, 0
	v_mov_b64_e32 v[94:95], v[42:43]
	v_mov_b64_e32 v[98:99], v[42:43]
	v_mov_b64_e32 v[102:103], v[42:43]
	v_mov_b64_e32 v[106:107], v[42:43]
	v_mov_b64_e32 v[110:111], v[42:43]
	v_mov_b64_e32 v[114:115], v[42:43]
	v_mov_b64_e32 v[118:119], v[42:43]
	v_mov_b64_e32 v[122:123], v[42:43]
	v_lshl_add_u32 v214, v207, 8, v2
	v_lshlrev_b32_e32 v215, 4, v211
	v_lshlrev_b32_e32 v216, 4, v208
	v_lshlrev_b32_e32 v219, 4, v0
	s_mov_b32 s25, 0
	v_mov_b32_e32 v220, 0
	v_mov_b64_e32 v[92:93], v[40:41]
	v_mov_b64_e32 v[96:97], v[40:41]
	v_mov_b64_e32 v[100:101], v[40:41]
	v_mov_b64_e32 v[104:105], v[40:41]
	v_mov_b64_e32 v[108:109], v[40:41]
	v_mov_b64_e32 v[112:113], v[40:41]
	v_mov_b64_e32 v[116:117], v[40:41]
	v_mov_b64_e32 v[120:121], v[40:41]
	s_mov_b32 s10, 0
	s_mov_b32 s11, 0
	v_mov_b32_e32 v0, 0
	v_mov_b32_e32 v1, v221
	v_mov_b32_e32 v2, v221
	v_mov_b32_e32 v3, v221
	v_mov_b32_e32 v4, v221
	v_mov_b32_e32 v5, v221
	v_mov_b32_e32 v6, v221
	v_mov_b32_e32 v7, v221
	v_xor_b32_e32 v226, 0x80000000, v221
	v_xor_b32_e32 v230, 0x80000000, v220
	v_mov_b32_e32 v222, s56
	v_mov_b32_e32 v227, v226
	v_mov_b32_e32 v231, v230
	v_mov_b32_e32 v223, v222
	v_mov_b32_e32 v228, v226
	v_mov_b32_e32 v232, v230
	v_mov_b32_e32 v224, v222
	v_mov_b32_e32 v229, v226
	v_mov_b32_e32 v233, v230
	v_mov_b32_e32 v225, v222

.Latt_h168:
	v_lshl_add_u32 v8, s10, 14, v214
	v_add_u32_e32 v38, v8, v217
	v_add_u32_e32 v39, v8, v218
	v_add_u32_e32 v40, v8, v219
	s_lshl_b32 s27, s10, 13
	s_and_b64 vcc, exec, s[4:5]
	s_cbranch_vccz .Latt_main
	s_cmp_eq_u32 s11, 0
	s_cbranch_scc1 .Latt_main
	s_add_i32 s2, s27, 0xffffe000
	s_cmp_lg_u32 s10, 0
	s_cselect_b32 s2, s2, 0xa000
	v_add_u32_e32 v8, s2, v210
	v_add_u32_e32 v42, v8, v215
	v_add_u32_e32 v43, v8, v216
	ds_read_b128 v[16:19], v42 offset:0
	ds_read_b128 v[20:23], v42 offset:2048
	ds_read_b128 v[24:27], v42 offset:4096
	ds_read_b128 v[28:31], v42 offset:6144
	ds_read_b128 v[188:191], v43 offset:0
	ds_read_b128 v[192:195], v43 offset:2048
	ds_read_b128 v[196:199], v43 offset:4096
	ds_read_b128 v[32:35], v43 offset:6144
	v_max3_f32 v36, v140, v141, v142
	v_max3_f32 v37, v124, v125, v126
	v_max3_f32 v36, v36, v143, v144
	v_max3_f32 v37, v37, v127, v128
	v_max3_f32 v36, v36, v145, v146
	v_max3_f32 v37, v37, v129, v130
	v_max3_f32 v36, v36, v147, v148
	v_max3_f32 v37, v37, v131, v132
	v_max3_f32 v36, v36, v149, v150
	v_max3_f32 v37, v37, v133, v134
	v_max3_f32 v36, v36, v151, v152
	v_max3_f32 v37, v37, v135, v136
	v_max3_f32 v36, v36, v153, v154
	v_max3_f32 v37, v37, v137, v138
	v_max3_f32 v36, v36, v155, v155
	v_max3_f32 v37, v37, v139, v139
	v_cmp_lt_f32_e32 vcc, s44, v36
	s_cbranch_vccnz .Latt_rare0_p
.Latt_c0_p:
	v_cmp_lt_f32_e32 vcc, s44, v37
	s_cbranch_vccnz .Latt_rare1_p
.Latt_c1_p:
	v_exp_f32_e32 v140, v140
	v_exp_f32_e32 v141, v141
	v_exp_f32_e32 v142, v142
	v_exp_f32_e32 v143, v143
	v_exp_f32_e32 v144, v144
	v_exp_f32_e32 v145, v145
	v_exp_f32_e32 v146, v146
	v_exp_f32_e32 v147, v147
	v_exp_f32_e32 v124, v124
	v_exp_f32_e32 v125, v125
	v_exp_f32_e32 v126, v126
	v_exp_f32_e32 v127, v127
	v_exp_f32_e32 v128, v128
	v_exp_f32_e32 v129, v129
	v_exp_f32_e32 v130, v130
	v_exp_f32_e32 v131, v131
	v_cvt_pk_bf16_f32 v140, v140, v141
	v_cvt_pk_bf16_f32 v141, v142, v143
	v_cvt_pk_bf16_f32 v142, v144, v145
	v_cvt_pk_bf16_f32 v143, v146, v147
	v_cvt_pk_bf16_f32 v124, v124, v125
	v_cvt_pk_bf16_f32 v125, v126, v127
	v_cvt_pk_bf16_f32 v126, v128, v129
	v_cvt_pk_bf16_f32 v127, v130, v131
	s_setprio 1
	s_waitcnt lgkmcnt(4)
	v_mfma_f32_16x16x32_bf16 v[92:95], v[16:19], v[140:143], v[92:95]
	v_exp_f32_e32 v148, v148
	v_exp_f32_e32 v149, v149
	v_mfma_f32_16x16x32_bf16 v[96:99], v[16:19], v[124:127], v[96:99]
	v_exp_f32_e32 v150, v150
	v_exp_f32_e32 v151, v151
	v_mfma_f32_16x16x32_bf16 v[100:103], v[20:23], v[140:143], v[100:103]
	v_exp_f32_e32 v152, v152
	v_exp_f32_e32 v153, v153
	v_mfma_f32_16x16x32_bf16 v[104:107], v[20:23], v[124:127], v[104:107]
	v_exp_f32_e32 v154, v154
	v_exp_f32_e32 v155, v155
	v_mfma_f32_16x16x32_bf16 v[108:111], v[24:27], v[140:143], v[108:111]
	v_cvt_pk_bf16_f32 v148, v148, v149
	v_cvt_pk_bf16_f32 v149, v150, v151
	v_mfma_f32_16x16x32_bf16 v[112:115], v[24:27], v[124:127], v[112:115]
	v_cvt_pk_bf16_f32 v150, v152, v153
	v_cvt_pk_bf16_f32 v151, v154, v155
	v_mfma_f32_16x16x32_bf16 v[116:119], v[28:31], v[140:143], v[116:119]
	v_exp_f32_e32 v132, v132
	v_exp_f32_e32 v133, v133
	v_mfma_f32_16x16x32_bf16 v[120:123], v[28:31], v[124:127], v[120:123]
	v_exp_f32_e32 v134, v134
	v_exp_f32_e32 v135, v135
	v_mfma_f32_16x16x32_bf16 v[0:3], v[222:225], v[140:143], v[0:3]
	v_exp_f32_e32 v136, v136
	v_exp_f32_e32 v137, v137
	v_mfma_f32_16x16x32_bf16 v[4:7], v[222:225], v[124:127], v[4:7]
	v_exp_f32_e32 v138, v138
	v_exp_f32_e32 v139, v139
	s_waitcnt lgkmcnt(0)
	v_mfma_f32_16x16x32_bf16 v[92:95], v[188:191], v[148:151], v[92:95]
	v_cvt_pk_bf16_f32 v132, v132, v133
	v_cvt_pk_bf16_f32 v133, v134, v135
	v_mfma_f32_16x16x32_bf16 v[100:103], v[192:195], v[148:151], v[100:103]
	v_cvt_pk_bf16_f32 v134, v136, v137
	v_cvt_pk_bf16_f32 v135, v138, v139
	v_mfma_f32_16x16x32_bf16 v[108:111], v[196:199], v[148:151], v[108:111]
	v_mfma_f32_16x16x32_bf16 v[116:119], v[32:35], v[148:151], v[116:119]
	v_mfma_f32_16x16x32_bf16 v[0:3], v[222:225], v[148:151], v[0:3]
	v_mfma_f32_16x16x32_bf16 v[96:99], v[188:191], v[132:135], v[96:99]
	v_mfma_f32_16x16x32_bf16 v[104:107], v[192:195], v[132:135], v[104:107]
	v_mfma_f32_16x16x32_bf16 v[112:115], v[196:199], v[132:135], v[112:115]
	v_mfma_f32_16x16x32_bf16 v[120:123], v[32:35], v[132:135], v[120:123]
	v_mfma_f32_16x16x32_bf16 v[4:7], v[222:225], v[132:135], v[4:7]
	s_setprio 0
.Latt_main:
	ds_read_b128 v[156:159], v38 offset:0
	ds_read_b128 v[160:163], v38 offset:4096
	ds_read_b128 v[164:167], v38 offset:8192
	ds_read_b128 v[168:171], v38 offset:12288
	ds_read_b128 v[172:175], v39 offset:0
	ds_read_b128 v[176:179], v39 offset:4096
	ds_read_b128 v[180:183], v39 offset:8192
	ds_read_b128 v[184:187], v39 offset:12288
	s_setprio 1
	s_waitcnt lgkmcnt(7)
	v_mfma_f32_16x16x32_bf16 v[140:143], v[156:159], v[44:47], v[226:229]
	v_mfma_f32_16x16x32_bf16 v[124:127], v[156:159], v[56:59], v[230:233]
	s_waitcnt lgkmcnt(6)
	v_mfma_f32_16x16x32_bf16 v[144:147], v[160:163], v[44:47], v[226:229]
	v_mfma_f32_16x16x32_bf16 v[128:131], v[160:163], v[56:59], v[230:233]
	s_waitcnt lgkmcnt(5)
	v_mfma_f32_16x16x32_bf16 v[148:151], v[164:167], v[44:47], v[226:229]
	v_mfma_f32_16x16x32_bf16 v[132:135], v[164:167], v[56:59], v[230:233]
	s_waitcnt lgkmcnt(4)
	v_mfma_f32_16x16x32_bf16 v[152:155], v[168:171], v[44:47], v[226:229]
	v_mfma_f32_16x16x32_bf16 v[136:139], v[168:171], v[56:59], v[230:233]
	s_waitcnt lgkmcnt(3)
	v_mfma_f32_16x16x32_bf16 v[140:143], v[172:175], v[48:51], v[140:143]
	v_mfma_f32_16x16x32_bf16 v[124:127], v[172:175], v[60:63], v[124:127]
	ds_read_b128 v[156:159], v40 offset:0
	ds_read_b128 v[160:163], v40 offset:4096
	ds_read_b128 v[164:167], v40 offset:8192
	ds_read_b128 v[168:171], v40 offset:12288
	s_waitcnt lgkmcnt(6)
	v_mfma_f32_16x16x32_bf16 v[144:147], v[176:179], v[48:51], v[144:147]
	v_mfma_f32_16x16x32_bf16 v[128:131], v[176:179], v[60:63], v[128:131]
	s_waitcnt lgkmcnt(5)
	v_mfma_f32_16x16x32_bf16 v[148:151], v[180:183], v[48:51], v[148:151]
	v_mfma_f32_16x16x32_bf16 v[132:135], v[180:183], v[60:63], v[132:135]
	s_waitcnt lgkmcnt(4)
	v_mfma_f32_16x16x32_bf16 v[152:155], v[184:187], v[48:51], v[152:155]
	v_mfma_f32_16x16x32_bf16 v[136:139], v[184:187], v[60:63], v[136:139]
	s_waitcnt lgkmcnt(3)
	v_mfma_f32_16x16x32_bf16 v[140:143], v[156:159], v[52:55], v[140:143]
	v_mfma_f32_16x16x32_bf16 v[124:127], v[156:159], v[64:67], v[124:127]
	s_waitcnt lgkmcnt(2)
	v_mfma_f32_16x16x32_bf16 v[144:147], v[160:163], v[52:55], v[144:147]
	v_mfma_f32_16x16x32_bf16 v[128:131], v[160:163], v[64:67], v[128:131]
	s_waitcnt lgkmcnt(1)
	v_mfma_f32_16x16x32_bf16 v[148:151], v[164:167], v[52:55], v[148:151]
	v_mfma_f32_16x16x32_bf16 v[132:135], v[164:167], v[64:67], v[132:135]
	s_waitcnt lgkmcnt(0)
	v_mfma_f32_16x16x32_bf16 v[152:155], v[168:171], v[52:55], v[152:155]
	v_mfma_f32_16x16x32_bf16 v[136:139], v[168:171], v[64:67], v[136:139]
	s_setprio 0
	v_add_u32_e32 v8, s27, v210
	v_add_u32_e32 v42, v8, v215
	v_add_u32_e32 v43, v8, v216
	ds_read_b128 v[16:19], v42 offset:0
	ds_read_b128 v[20:23], v42 offset:2048
	ds_read_b128 v[24:27], v42 offset:4096
	ds_read_b128 v[28:31], v42 offset:6144
	ds_read_b128 v[188:191], v43 offset:0
	ds_read_b128 v[192:195], v43 offset:2048
	ds_read_b128 v[196:199], v43 offset:4096
	ds_read_b128 v[32:35], v43 offset:6144
	v_max3_f32 v36, v140, v141, v142
	v_max3_f32 v37, v124, v125, v126
	v_max3_f32 v36, v36, v143, v144
	v_max3_f32 v37, v37, v127, v128
	v_max3_f32 v36, v36, v145, v146
	v_max3_f32 v37, v37, v129, v130
	v_max3_f32 v36, v36, v147, v148
	v_max3_f32 v37, v37, v131, v132
	v_max3_f32 v36, v36, v149, v150
	v_max3_f32 v37, v37, v133, v134
	v_max3_f32 v36, v36, v151, v152
	v_max3_f32 v37, v37, v135, v136
	v_max3_f32 v36, v36, v153, v154
	v_max3_f32 v37, v37, v137, v138
	v_max3_f32 v36, v36, v155, v155
	v_max3_f32 v37, v37, v139, v139
	s_cmp_eq_u32 s11, 0
	s_cbranch_scc1 .Latt_rare0_a
	v_cmp_lt_f32_e32 vcc, s44, v36
	s_cbranch_vccnz .Latt_rare0_a
.Latt_c0_a:
	s_cmp_eq_u32 s11, 0
	s_cbranch_scc1 .Latt_rare1_a
	v_cmp_lt_f32_e32 vcc, s44, v37
	s_cbranch_vccnz .Latt_rare1_a
.Latt_c1_a:
	v_exp_f32_e32 v140, v140
	v_exp_f32_e32 v141, v141
	v_exp_f32_e32 v142, v142
	v_exp_f32_e32 v143, v143
	v_exp_f32_e32 v144, v144
	v_exp_f32_e32 v145, v145
	v_exp_f32_e32 v146, v146
	v_exp_f32_e32 v147, v147
	v_exp_f32_e32 v124, v124
	v_exp_f32_e32 v125, v125
	v_exp_f32_e32 v126, v126
	v_exp_f32_e32 v127, v127
	v_exp_f32_e32 v128, v128
	v_exp_f32_e32 v129, v129
	v_exp_f32_e32 v130, v130
	v_exp_f32_e32 v131, v131
	v_cvt_pk_bf16_f32 v140, v140, v141
	v_cvt_pk_bf16_f32 v141, v142, v143
	v_cvt_pk_bf16_f32 v142, v144, v145
	v_cvt_pk_bf16_f32 v143, v146, v147
	v_cvt_pk_bf16_f32 v124, v124, v125
	v_cvt_pk_bf16_f32 v125, v126, v127
	v_cvt_pk_bf16_f32 v126, v128, v129
	v_cvt_pk_bf16_f32 v127, v130, v131
	s_setprio 1
	s_waitcnt lgkmcnt(4)
	v_mfma_f32_16x16x32_bf16 v[92:95], v[16:19], v[140:143], v[92:95]
	v_exp_f32_e32 v148, v148
	v_exp_f32_e32 v149, v149
	v_mfma_f32_16x16x32_bf16 v[96:99], v[16:19], v[124:127], v[96:99]
	v_exp_f32_e32 v150, v150
	v_exp_f32_e32 v151, v151
	v_mfma_f32_16x16x32_bf16 v[100:103], v[20:23], v[140:143], v[100:103]
	v_exp_f32_e32 v152, v152
	v_exp_f32_e32 v153, v153
	v_mfma_f32_16x16x32_bf16 v[104:107], v[20:23], v[124:127], v[104:107]
	v_exp_f32_e32 v154, v154
	v_exp_f32_e32 v155, v155
	v_mfma_f32_16x16x32_bf16 v[108:111], v[24:27], v[140:143], v[108:111]
	v_cvt_pk_bf16_f32 v148, v148, v149
	v_cvt_pk_bf16_f32 v149, v150, v151
	v_mfma_f32_16x16x32_bf16 v[112:115], v[24:27], v[124:127], v[112:115]
	v_cvt_pk_bf16_f32 v150, v152, v153
	v_cvt_pk_bf16_f32 v151, v154, v155
	v_mfma_f32_16x16x32_bf16 v[116:119], v[28:31], v[140:143], v[116:119]
	v_exp_f32_e32 v132, v132
	v_exp_f32_e32 v133, v133
	v_mfma_f32_16x16x32_bf16 v[120:123], v[28:31], v[124:127], v[120:123]
	v_exp_f32_e32 v134, v134
	v_exp_f32_e32 v135, v135
	v_mfma_f32_16x16x32_bf16 v[0:3], v[222:225], v[140:143], v[0:3]
	v_exp_f32_e32 v136, v136
	v_exp_f32_e32 v137, v137
	v_mfma_f32_16x16x32_bf16 v[4:7], v[222:225], v[124:127], v[4:7]
	v_exp_f32_e32 v138, v138
	v_exp_f32_e32 v139, v139
	s_waitcnt lgkmcnt(0)
	v_mfma_f32_16x16x32_bf16 v[92:95], v[188:191], v[148:151], v[92:95]
	v_cvt_pk_bf16_f32 v132, v132, v133
	v_cvt_pk_bf16_f32 v133, v134, v135
	v_mfma_f32_16x16x32_bf16 v[100:103], v[192:195], v[148:151], v[100:103]
	v_cvt_pk_bf16_f32 v134, v136, v137
	v_cvt_pk_bf16_f32 v135, v138, v139
	v_mfma_f32_16x16x32_bf16 v[108:111], v[196:199], v[148:151], v[108:111]
	v_mfma_f32_16x16x32_bf16 v[116:119], v[32:35], v[148:151], v[116:119]
	v_mfma_f32_16x16x32_bf16 v[0:3], v[222:225], v[148:151], v[0:3]
	v_mfma_f32_16x16x32_bf16 v[96:99], v[188:191], v[132:135], v[96:99]
	v_mfma_f32_16x16x32_bf16 v[104:107], v[192:195], v[132:135], v[104:107]
	v_mfma_f32_16x16x32_bf16 v[112:115], v[196:199], v[132:135], v[112:115]
	v_mfma_f32_16x16x32_bf16 v[120:123], v[32:35], v[132:135], v[120:123]
	v_mfma_f32_16x16x32_bf16 v[4:7], v[222:225], v[132:135], v[4:7]
	s_setprio 0
	ds_read_b128 v[156:159], v38 offset:16384
	ds_read_b128 v[160:163], v38 offset:20480
	ds_read_b128 v[164:167], v38 offset:24576
	ds_read_b128 v[168:171], v38 offset:28672
	ds_read_b128 v[172:175], v39 offset:16384
	ds_read_b128 v[176:179], v39 offset:20480
	ds_read_b128 v[180:183], v39 offset:24576
	ds_read_b128 v[184:187], v39 offset:28672
	s_setprio 1
	s_waitcnt lgkmcnt(7)
	v_mfma_f32_16x16x32_bf16 v[140:143], v[156:159], v[44:47], v[226:229]
	v_mfma_f32_16x16x32_bf16 v[124:127], v[156:159], v[56:59], v[230:233]
	s_waitcnt lgkmcnt(6)
	v_mfma_f32_16x16x32_bf16 v[144:147], v[160:163], v[44:47], v[226:229]
	v_mfma_f32_16x16x32_bf16 v[128:131], v[160:163], v[56:59], v[230:233]
	s_waitcnt lgkmcnt(5)
	v_mfma_f32_16x16x32_bf16 v[148:151], v[164:167], v[44:47], v[226:229]
	v_mfma_f32_16x16x32_bf16 v[132:135], v[164:167], v[56:59], v[230:233]
	s_waitcnt lgkmcnt(4)
	v_mfma_f32_16x16x32_bf16 v[152:155], v[168:171], v[44:47], v[226:229]
	v_mfma_f32_16x16x32_bf16 v[136:139], v[168:171], v[56:59], v[230:233]
	s_waitcnt lgkmcnt(3)
	v_mfma_f32_16x16x32_bf16 v[140:143], v[172:175], v[48:51], v[140:143]
	v_mfma_f32_16x16x32_bf16 v[124:127], v[172:175], v[60:63], v[124:127]
	ds_read_b128 v[156:159], v40 offset:16384
	ds_read_b128 v[160:163], v40 offset:20480
	ds_read_b128 v[164:167], v40 offset:24576
	ds_read_b128 v[168:171], v40 offset:28672
	s_waitcnt lgkmcnt(6)
	v_mfma_f32_16x16x32_bf16 v[144:147], v[176:179], v[48:51], v[144:147]
	v_mfma_f32_16x16x32_bf16 v[128:131], v[176:179], v[60:63], v[128:131]
	s_waitcnt lgkmcnt(5)
	v_mfma_f32_16x16x32_bf16 v[148:151], v[180:183], v[48:51], v[148:151]
	v_mfma_f32_16x16x32_bf16 v[132:135], v[180:183], v[60:63], v[132:135]
	s_waitcnt lgkmcnt(4)
	v_mfma_f32_16x16x32_bf16 v[152:155], v[184:187], v[48:51], v[152:155]
	v_mfma_f32_16x16x32_bf16 v[136:139], v[184:187], v[60:63], v[136:139]
	s_waitcnt lgkmcnt(3)
	v_mfma_f32_16x16x32_bf16 v[140:143], v[156:159], v[52:55], v[140:143]
	v_mfma_f32_16x16x32_bf16 v[124:127], v[156:159], v[64:67], v[124:127]
	s_waitcnt lgkmcnt(2)
	v_mfma_f32_16x16x32_bf16 v[144:147], v[160:163], v[52:55], v[144:147]
	v_mfma_f32_16x16x32_bf16 v[128:131], v[160:163], v[64:67], v[128:131]
	s_waitcnt lgkmcnt(1)
	v_mfma_f32_16x16x32_bf16 v[148:151], v[164:167], v[52:55], v[148:151]
	v_mfma_f32_16x16x32_bf16 v[132:135], v[164:167], v[64:67], v[132:135]
	s_waitcnt lgkmcnt(0)
	v_mfma_f32_16x16x32_bf16 v[152:155], v[168:171], v[52:55], v[152:155]
	v_mfma_f32_16x16x32_bf16 v[136:139], v[168:171], v[64:67], v[136:139]
	s_setprio 0
	s_and_b64 vcc, exec, s[4:5]
	s_cbranch_vccnz .Latt_tail
	ds_read_b128 v[16:19], v42 offset:8192
	ds_read_b128 v[20:23], v42 offset:10240
	ds_read_b128 v[24:27], v42 offset:12288
	ds_read_b128 v[28:31], v42 offset:14336
	ds_read_b128 v[188:191], v43 offset:8192
	ds_read_b128 v[192:195], v43 offset:10240
	ds_read_b128 v[196:199], v43 offset:12288
	ds_read_b128 v[32:35], v43 offset:14336
	v_max3_f32 v36, v140, v141, v142
	v_max3_f32 v37, v124, v125, v126
	v_max3_f32 v36, v36, v143, v144
	v_max3_f32 v37, v37, v127, v128
	v_max3_f32 v36, v36, v145, v146
	v_max3_f32 v37, v37, v129, v130
	v_max3_f32 v36, v36, v147, v148
	v_max3_f32 v37, v37, v131, v132
	v_max3_f32 v36, v36, v149, v150
	v_max3_f32 v37, v37, v133, v134
	v_max3_f32 v36, v36, v151, v152
	v_max3_f32 v37, v37, v135, v136
	v_max3_f32 v36, v36, v153, v154
	v_max3_f32 v37, v37, v137, v138
	v_max3_f32 v36, v36, v155, v155
	v_max3_f32 v37, v37, v139, v139
	v_cmp_lt_f32_e32 vcc, s44, v36
	s_cbranch_vccnz .Latt_rare0_b

; #define ABAR() { asm volatile("s_waitcnt lgkmcnt(0)" ::: "memory"); __builtin_amdgcn_s_barrier(); asm volatile("" ::: "memory"); }
; DEV void attn_item(const P& p, int bh, int qrow0, int nkt, int outrow0, char* smem) {
;     ...
;     ABAR();
;     s0 = sn;
;   }
.Latt_tail:
	s_waitcnt lgkmcnt(0)
	s_barrier
	s_addk_i32 s25, 0x80
	s_cmp_eq_u32 s23, s26
	s_cbranch_scc1 .Latt_exit
	s_mov_b32 s10, s24
	s_mov_b32 s11, s26
	s_branch .Latt_loop
.Latt_rare0_p:
	v_xor_b32_e32 v10, 16, v237
	v_lshlrev_b32_e32 v10, 2, v10
	ds_bpermute_b32 v10, v10, v36
	v_xor_b32_e32 v12, 32, v237
	v_lshlrev_b32_e32 v12, 2, v12
	v_max_f32_e32 v11, v36, v36
	s_waitcnt lgkmcnt(0)
	v_max_f32_e32 v10, v10, v10
	v_max_f32_e32 v11, v11, v10
	s_nop 0
	ds_bpermute_b32 v10, v12, v11
	s_waitcnt lgkmcnt(0)
	v_max_f32_e32 v10, v10, v10
	v_max_f32_e32 v11, v11, v10
	v_exp_f32_e64 v8, -v11
	v_add_f32_e32 v221, v221, v11
	v_xor_b32_e32 v226, 0x80000000, v221
	v_sub_f32_e32 v140, v140, v11
	v_sub_f32_e32 v141, v141, v11
	v_sub_f32_e32 v142, v142, v11
	v_sub_f32_e32 v143, v143, v11
	v_sub_f32_e32 v144, v144, v11
	v_sub_f32_e32 v145, v145, v11
	v_sub_f32_e32 v146, v146, v11
	v_sub_f32_e32 v147, v147, v11
	v_sub_f32_e32 v148, v148, v11
	v_sub_f32_e32 v149, v149, v11
	v_sub_f32_e32 v150, v150, v11
	v_sub_f32_e32 v151, v151, v11
	v_sub_f32_e32 v152, v152, v11
	v_sub_f32_e32 v153, v153, v11
	v_sub_f32_e32 v154, v154, v11
	v_sub_f32_e32 v155, v155, v11
	v_mov_b32_e32 v227, v226
	v_mov_b32_e32 v228, v226
	v_mov_b32_e32 v229, v226
	v_pk_mul_f32 v[92:93], v[92:93], v[8:9] op_sel_hi:[1,0]
	v_pk_mul_f32 v[94:95], v[94:95], v[8:9] op_sel_hi:[1,0]
	v_pk_mul_f32 v[100:101], v[100:101], v[8:9] op_sel_hi:[1,0]
	v_pk_mul_f32 v[102:103], v[102:103], v[8:9] op_sel_hi:[1,0]
	v_pk_mul_f32 v[108:109], v[108:109], v[8:9] op_sel_hi:[1,0]
	v_pk_mul_f32 v[110:111], v[110:111], v[8:9] op_sel_hi:[1,0]
	v_pk_mul_f32 v[116:117], v[116:117], v[8:9] op_sel_hi:[1,0]
	v_pk_mul_f32 v[118:119], v[118:119], v[8:9] op_sel_hi:[1,0]
	v_pk_mul_f32 v[0:1], v[0:1], v[8:9] op_sel_hi:[1,0]
	v_pk_mul_f32 v[2:3], v[2:3], v[8:9] op_sel_hi:[1,0]
	s_branch .Latt_c0_p
.Latt_rare1_p:
	v_xor_b32_e32 v10, 16, v237
	v_lshlrev_b32_e32 v10, 2, v10
	ds_bpermute_b32 v10, v10, v37
	v_xor_b32_e32 v12, 32, v237
	v_lshlrev_b32_e32 v12, 2, v12
	v_max_f32_e32 v11, v37, v37
	s_waitcnt lgkmcnt(0)
	v_max_f32_e32 v10, v10, v10
	v_max_f32_e32 v11, v11, v10
	s_nop 0
	ds_bpermute_b32 v10, v12, v11
	s_waitcnt lgkmcnt(0)
	v_max_f32_e32 v10, v10, v10
	v_max_f32_e32 v11, v11, v10
	v_exp_f32_e64 v8, -v11
	v_add_f32_e32 v220, v220, v11
	v_xor_b32_e32 v230, 0x80000000, v220
	v_sub_f32_e32 v124, v124, v11
	v_sub_f32_e32 v125, v125, v11
	v_sub_f32_e32 v126, v126, v11
	v_sub_f32_e32 v127, v127, v11
	v_sub_f32_e32 v128, v128, v11
	v_sub_f32_e32 v129, v129, v11
	v_sub_f32_e32 v130, v130, v11
	v_sub_f32_e32 v131, v131, v11
	v_sub_f32_e32 v132, v132, v11
	v_sub_f32_e32 v133, v133, v11
	v_sub_f32_e32 v134, v134, v11
	v_sub_f32_e32 v135, v135, v11
	v_sub_f32_e32 v136, v136, v11
	v_sub_f32_e32 v137, v137, v11
	v_sub_f32_e32 v138, v138, v11
	v_sub_f32_e32 v139, v139, v11
	v_mov_b32_e32 v231, v230
	v_mov_b32_e32 v232, v230
	v_mov_b32_e32 v233, v230
	v_pk_mul_f32 v[96:97], v[96:97], v[8:9] op_sel_hi:[1,0]
	v_pk_mul_f32 v[98:99], v[98:99], v[8:9] op_sel_hi:[1,0]
	v_pk_mul_f32 v[104:105], v[104:105], v[8:9] op_sel_hi:[1,0]
	v_pk_mul_f32 v[106:107], v[106:107], v[8:9] op_sel_hi:[1,0]
	v_pk_mul_f32 v[112:113], v[112:113], v[8:9] op_sel_hi:[1,0]
	v_pk_mul_f32 v[114:115], v[114:115], v[8:9] op_sel_hi:[1,0]
	v_pk_mul_f32 v[120:121], v[120:121], v[8:9] op_sel_hi:[1,0]
	v_pk_mul_f32 v[122:123], v[122:123], v[8:9] op_sel_hi:[1,0]
	v_pk_mul_f32 v[4:5], v[4:5], v[8:9] op_sel_hi:[1,0]
	v_pk_mul_f32 v[6:7], v[6:7], v[8:9] op_sel_hi:[1,0]
	s_branch .Latt_c1_p

; DEV unsigned pk_bf16(float lo, float hi) { unsigned r; asm("v_cvt_pk_bf16_f32 %0, %1, %2" : "=v"(r) : "v"(lo), "v"(hi)); return r; }
; #define PVLOAD(slot) { const char* s = smem + (slot) * VB; \
;     _Pragma("unroll") for (int vt = 0; vt < 4; ++vt) vf[0][vt] = *(const bf16x8*)(s + vt * 2048 + vro + (((0 * 4 + lq) ^ (l15 >> 1)) << 4)); }
; #define ABAR() { asm volatile("s_waitcnt lgkmcnt(0)" ::: "memory"); __builtin_amdgcn_s_barrier(); asm volatile("" ::: "memory"); }
; DEV void attn_item(const P& p, int bh, int qrow0, int nkt, int outrow0, char* smem) {
;     ...
;   if (skew) { const int sp = (s0 == 0) ? 5 : s0 - 1; PVLOAD(sp); SM(false); PVMMA(sp); }
;   ABAR();
;     ...
;   const int h = bh & 7;
; #pragma unroll
;   for (int qt = 0; qt < 2; ++qt) {
;     const float inv = 1.0f / osum[qt][0];
;     const int row = outrow0 + wid * 32 + qt * 16 + l15;
; #pragma unroll
;     for (int vt = 0; vt < 4; ++vt) {
;       const f32x4 v = o[vt][qt] * inv;
;       *(u32x2*)(Z + (size_t)row * LDZ + ZAO + h * 64 + vt * 16 + lq * 4) = (u32x2){pk_bf16(v[0], v[1]), pk_bf16(v[2], v[3])};
;     }
;   }
.Latt_exit:
	s_nop 7
	v_mov_b64_e32 v[176:177], v[92:93]
	v_mov_b64_e32 v[178:179], v[94:95]
	v_mov_b64_e32 v[172:173], v[100:101]
	v_mov_b64_e32 v[174:175], v[102:103]
	v_mov_b64_e32 v[168:169], v[108:109]
	v_mov_b64_e32 v[170:171], v[110:111]
	v_mov_b64_e32 v[164:165], v[116:117]
	v_mov_b64_e32 v[166:167], v[118:119]
	v_mov_b64_e32 v[160:161], v[96:97]
	v_mov_b64_e32 v[162:163], v[98:99]
	v_mov_b64_e32 v[156:157], v[104:105]
	v_mov_b64_e32 v[158:159], v[106:107]
	v_mov_b64_e32 v[36:37], v[112:113]
	v_mov_b64_e32 v[38:39], v[114:115]
	v_mov_b64_e32 v[32:33], v[120:121]
	v_mov_b64_e32 v[34:35], v[122:123]
	v_mov_b64_e32 v[22:23], v[4:5]
	v_mov_b64_e32 v[24:25], v[6:7]
	v_mov_b32_e32 v40, v221
	v_mov_b32_e32 v42, v220
	s_branch .LBB0_215
